# gather u-dot: horizontal add tail reduced from 3 moves + packed add + add to 3 scalar adds (bit-identical)
# speedup vs baseline: 1.1732x; 1.0056x over previous
.LBB0_330:
	s_waitcnt vmcnt(22)
	v_cvt_scalef32_pk32_f32_fp6 v[0:31], v[32:37], 1.0
	v_pk_fma_f32 v[0:1], v[0:1], v[152:153], 0 op_sel_hi:[1,1,0]
	v_pk_fma_f32 v[2:3], v[2:3], v[170:171], 0 op_sel_hi:[1,1,0]
	v_pk_fma_f32 v[0:1], v[4:5], v[148:149], v[0:1]
	v_pk_fma_f32 v[2:3], v[6:7], v[172:173], v[2:3]
	v_pk_fma_f32 v[0:1], v[8:9], v[144:145], v[0:1]
	v_pk_fma_f32 v[2:3], v[10:11], v[174:175], v[2:3]
	v_pk_fma_f32 v[0:1], v[12:13], v[140:141], v[0:1]
	v_pk_fma_f32 v[2:3], v[14:15], v[178:179], v[2:3]
	v_pk_fma_f32 v[0:1], v[16:17], v[168:169], v[0:1]
	v_pk_fma_f32 v[2:3], v[18:19], v[180:181], v[2:3]
	v_pk_fma_f32 v[0:1], v[20:21], v[164:165], v[0:1]
	v_pk_fma_f32 v[2:3], v[22:23], v[182:183], v[2:3]
	v_pk_fma_f32 v[0:1], v[24:25], v[160:161], v[0:1]
	v_pk_fma_f32 v[2:3], v[26:27], v[184:185], v[2:3]
	v_pk_fma_f32 v[0:1], v[28:29], v[156:157], v[0:1]
	v_pk_fma_f32 v[2:3], v[30:31], v[186:187], v[2:3]
	v_add_f32_e32 v4, v2, v3
	v_add_f32_e32 v5, v0, v1
	v_add_f32_e32 v117, v4, v5
	s_waitcnt vmcnt(20)
	v_cvt_scalef32_pk32_f32_fp6 v[0:31], v[38:43], 1.0
	v_pk_fma_f32 v[0:1], v[0:1], v[152:153], 0 op_sel_hi:[1,1,0]
	v_pk_fma_f32 v[2:3], v[2:3], v[170:171], 0 op_sel_hi:[1,1,0]
	v_pk_fma_f32 v[0:1], v[4:5], v[148:149], v[0:1]
	v_pk_fma_f32 v[2:3], v[6:7], v[172:173], v[2:3]
	v_pk_fma_f32 v[0:1], v[8:9], v[144:145], v[0:1]
	v_pk_fma_f32 v[2:3], v[10:11], v[174:175], v[2:3]
	v_pk_fma_f32 v[0:1], v[12:13], v[140:141], v[0:1]
	v_pk_fma_f32 v[2:3], v[14:15], v[178:179], v[2:3]
	v_pk_fma_f32 v[0:1], v[16:17], v[168:169], v[0:1]
	v_pk_fma_f32 v[2:3], v[18:19], v[180:181], v[2:3]
	v_pk_fma_f32 v[0:1], v[20:21], v[164:165], v[0:1]
	v_pk_fma_f32 v[2:3], v[22:23], v[182:183], v[2:3]
	v_pk_fma_f32 v[0:1], v[24:25], v[160:161], v[0:1]
	v_pk_fma_f32 v[2:3], v[26:27], v[184:185], v[2:3]
	v_pk_fma_f32 v[0:1], v[28:29], v[156:157], v[0:1]
	v_pk_fma_f32 v[2:3], v[30:31], v[186:187], v[2:3]
	v_add_f32_e32 v4, v2, v3
	v_add_f32_e32 v5, v0, v1
	v_add_f32_e32 v131, v4, v5
	s_waitcnt vmcnt(18)
	v_cvt_scalef32_pk32_f32_fp6 v[0:31], v[44:49], 1.0
	v_pk_fma_f32 v[0:1], v[0:1], v[152:153], 0 op_sel_hi:[1,1,0]
	v_pk_fma_f32 v[2:3], v[2:3], v[170:171], 0 op_sel_hi:[1,1,0]
	v_pk_fma_f32 v[0:1], v[4:5], v[148:149], v[0:1]
	v_pk_fma_f32 v[2:3], v[6:7], v[172:173], v[2:3]
	v_pk_fma_f32 v[0:1], v[8:9], v[144:145], v[0:1]
	v_pk_fma_f32 v[2:3], v[10:11], v[174:175], v[2:3]
	v_pk_fma_f32 v[0:1], v[12:13], v[140:141], v[0:1]
	v_pk_fma_f32 v[2:3], v[14:15], v[178:179], v[2:3]
	v_pk_fma_f32 v[0:1], v[16:17], v[168:169], v[0:1]
	v_pk_fma_f32 v[2:3], v[18:19], v[180:181], v[2:3]
	v_pk_fma_f32 v[0:1], v[20:21], v[164:165], v[0:1]
	v_pk_fma_f32 v[2:3], v[22:23], v[182:183], v[2:3]
	v_pk_fma_f32 v[0:1], v[24:25], v[160:161], v[0:1]
	v_pk_fma_f32 v[2:3], v[26:27], v[184:185], v[2:3]
	v_pk_fma_f32 v[0:1], v[28:29], v[156:157], v[0:1]
	v_pk_fma_f32 v[2:3], v[30:31], v[186:187], v[2:3]
	v_add_f32_e32 v4, v2, v3
	v_add_f32_e32 v5, v0, v1
	v_add_f32_e32 v133, v4, v5
	s_waitcnt vmcnt(16)
	v_cvt_scalef32_pk32_f32_fp6 v[0:31], v[50:55], 1.0
	v_pk_fma_f32 v[0:1], v[0:1], v[152:153], 0 op_sel_hi:[1,1,0]
	v_pk_fma_f32 v[2:3], v[2:3], v[170:171], 0 op_sel_hi:[1,1,0]
	v_pk_fma_f32 v[0:1], v[4:5], v[148:149], v[0:1]
	v_pk_fma_f32 v[2:3], v[6:7], v[172:173], v[2:3]
	v_pk_fma_f32 v[0:1], v[8:9], v[144:145], v[0:1]
	v_pk_fma_f32 v[2:3], v[10:11], v[174:175], v[2:3]
	v_pk_fma_f32 v[0:1], v[12:13], v[140:141], v[0:1]
	v_pk_fma_f32 v[2:3], v[14:15], v[178:179], v[2:3]
	v_pk_fma_f32 v[0:1], v[16:17], v[168:169], v[0:1]
	v_pk_fma_f32 v[2:3], v[18:19], v[180:181], v[2:3]
	v_pk_fma_f32 v[0:1], v[20:21], v[164:165], v[0:1]
	v_pk_fma_f32 v[2:3], v[22:23], v[182:183], v[2:3]
	v_pk_fma_f32 v[0:1], v[24:25], v[160:161], v[0:1]
	v_pk_fma_f32 v[2:3], v[26:27], v[184:185], v[2:3]
	v_pk_fma_f32 v[0:1], v[28:29], v[156:157], v[0:1]
	v_pk_fma_f32 v[2:3], v[30:31], v[186:187], v[2:3]
	v_add_f32_e32 v4, v2, v3
	v_add_f32_e32 v5, v0, v1
	v_add_f32_e32 v218, v4, v5
	s_waitcnt vmcnt(14)
	v_cvt_scalef32_pk32_f32_fp6 v[0:31], v[56:61], 1.0
	v_pk_fma_f32 v[0:1], v[0:1], v[152:153], 0 op_sel_hi:[1,1,0]
	v_pk_fma_f32 v[2:3], v[2:3], v[170:171], 0 op_sel_hi:[1,1,0]
	v_pk_fma_f32 v[0:1], v[4:5], v[148:149], v[0:1]
	v_pk_fma_f32 v[2:3], v[6:7], v[172:173], v[2:3]
	v_pk_fma_f32 v[0:1], v[8:9], v[144:145], v[0:1]
	v_pk_fma_f32 v[2:3], v[10:11], v[174:175], v[2:3]
	v_pk_fma_f32 v[0:1], v[12:13], v[140:141], v[0:1]
	v_pk_fma_f32 v[2:3], v[14:15], v[178:179], v[2:3]
	v_pk_fma_f32 v[0:1], v[16:17], v[168:169], v[0:1]
	v_pk_fma_f32 v[2:3], v[18:19], v[180:181], v[2:3]
	v_pk_fma_f32 v[0:1], v[20:21], v[164:165], v[0:1]
	v_pk_fma_f32 v[2:3], v[22:23], v[182:183], v[2:3]
	v_pk_fma_f32 v[0:1], v[24:25], v[160:161], v[0:1]
	v_pk_fma_f32 v[2:3], v[26:27], v[184:185], v[2:3]
	v_pk_fma_f32 v[0:1], v[28:29], v[156:157], v[0:1]
	v_pk_fma_f32 v[2:3], v[30:31], v[186:187], v[2:3]
	v_add_f32_e32 v4, v2, v3
	v_add_f32_e32 v5, v0, v1
	v_add_f32_e32 v219, v4, v5
	s_waitcnt vmcnt(12)
	v_cvt_scalef32_pk32_f32_fp6 v[0:31], v[62:67], 1.0
	v_pk_fma_f32 v[0:1], v[0:1], v[152:153], 0 op_sel_hi:[1,1,0]
	v_pk_fma_f32 v[2:3], v[2:3], v[170:171], 0 op_sel_hi:[1,1,0]
	v_pk_fma_f32 v[0:1], v[4:5], v[148:149], v[0:1]
	v_pk_fma_f32 v[2:3], v[6:7], v[172:173], v[2:3]
	v_pk_fma_f32 v[0:1], v[8:9], v[144:145], v[0:1]
	v_pk_fma_f32 v[2:3], v[10:11], v[174:175], v[2:3]
	v_pk_fma_f32 v[0:1], v[12:13], v[140:141], v[0:1]
	v_pk_fma_f32 v[2:3], v[14:15], v[178:179], v[2:3]
	v_pk_fma_f32 v[0:1], v[16:17], v[168:169], v[0:1]
	v_pk_fma_f32 v[2:3], v[18:19], v[180:181], v[2:3]
	v_pk_fma_f32 v[0:1], v[20:21], v[164:165], v[0:1]
	v_pk_fma_f32 v[2:3], v[22:23], v[182:183], v[2:3]
	v_pk_fma_f32 v[0:1], v[24:25], v[160:161], v[0:1]
	v_pk_fma_f32 v[2:3], v[26:27], v[184:185], v[2:3]
	v_pk_fma_f32 v[0:1], v[28:29], v[156:157], v[0:1]
	v_pk_fma_f32 v[2:3], v[30:31], v[186:187], v[2:3]
	v_add_f32_e32 v4, v2, v3
	v_add_f32_e32 v5, v0, v1
	v_add_f32_e32 v246, v4, v5
	s_waitcnt vmcnt(10)
	v_cvt_scalef32_pk32_f32_fp6 v[0:31], v[68:73], 1.0
	v_pk_fma_f32 v[0:1], v[0:1], v[152:153], 0 op_sel_hi:[1,1,0]
	v_pk_fma_f32 v[2:3], v[2:3], v[170:171], 0 op_sel_hi:[1,1,0]
	v_pk_fma_f32 v[0:1], v[4:5], v[148:149], v[0:1]
	v_pk_fma_f32 v[2:3], v[6:7], v[172:173], v[2:3]
	v_pk_fma_f32 v[0:1], v[8:9], v[144:145], v[0:1]
	v_pk_fma_f32 v[2:3], v[10:11], v[174:175], v[2:3]
	v_pk_fma_f32 v[0:1], v[12:13], v[140:141], v[0:1]
	v_pk_fma_f32 v[2:3], v[14:15], v[178:179], v[2:3]
	v_pk_fma_f32 v[0:1], v[16:17], v[168:169], v[0:1]
	v_pk_fma_f32 v[2:3], v[18:19], v[180:181], v[2:3]
	v_pk_fma_f32 v[0:1], v[20:21], v[164:165], v[0:1]
	v_pk_fma_f32 v[2:3], v[22:23], v[182:183], v[2:3]
	v_pk_fma_f32 v[0:1], v[24:25], v[160:161], v[0:1]
	v_pk_fma_f32 v[2:3], v[26:27], v[184:185], v[2:3]
	v_pk_fma_f32 v[0:1], v[28:29], v[156:157], v[0:1]
	v_pk_fma_f32 v[2:3], v[30:31], v[186:187], v[2:3]
	v_add_f32_e32 v4, v2, v3
	v_add_f32_e32 v5, v0, v1
	v_add_f32_e32 v247, v4, v5
	s_waitcnt vmcnt(8)
	v_cvt_scalef32_pk32_f32_fp6 v[0:31], v[74:79], 1.0
	v_pk_fma_f32 v[0:1], v[0:1], v[152:153], 0 op_sel_hi:[1,1,0]
	v_pk_fma_f32 v[2:3], v[2:3], v[170:171], 0 op_sel_hi:[1,1,0]
	v_pk_fma_f32 v[0:1], v[4:5], v[148:149], v[0:1]
	v_pk_fma_f32 v[2:3], v[6:7], v[172:173], v[2:3]
	v_pk_fma_f32 v[0:1], v[8:9], v[144:145], v[0:1]
	v_pk_fma_f32 v[2:3], v[10:11], v[174:175], v[2:3]
	v_pk_fma_f32 v[0:1], v[12:13], v[140:141], v[0:1]
	v_pk_fma_f32 v[2:3], v[14:15], v[178:179], v[2:3]
	v_pk_fma_f32 v[0:1], v[16:17], v[168:169], v[0:1]
	v_pk_fma_f32 v[2:3], v[18:19], v[180:181], v[2:3]
	v_pk_fma_f32 v[0:1], v[20:21], v[164:165], v[0:1]
	v_pk_fma_f32 v[2:3], v[22:23], v[182:183], v[2:3]
	v_pk_fma_f32 v[0:1], v[24:25], v[160:161], v[0:1]
	v_pk_fma_f32 v[2:3], v[26:27], v[184:185], v[2:3]
	v_pk_fma_f32 v[0:1], v[28:29], v[156:157], v[0:1]
	v_pk_fma_f32 v[2:3], v[30:31], v[186:187], v[2:3]
	v_add_f32_e32 v4, v2, v3
	v_add_f32_e32 v5, v0, v1
	v_add_f32_e32 v1, v4, v5
	v_add_u32_e32 v8, s24, v239
	ds_read_b32 v0, v8 offset:512
	s_waitcnt lgkmcnt(0)
	v_readlane_b32 s2, v0, 0
	v_readlane_b32 s3, v0, 32
	v_readlane_b32 s25, v0, 4
	v_readlane_b32 s26, v0, 36
	v_readlane_b32 s27, v0, 8
	v_readlane_b32 s30, v0, 40
	v_readlane_b32 s31, v0, 12
	v_readlane_b32 s34, v0, 44
	v_readlane_b32 s35, v0, 16
	v_readlane_b32 s36, v0, 48
	v_readlane_b32 s37, v0, 20
	v_readlane_b32 s38, v0, 52
	v_readlane_b32 s39, v0, 24
	v_readlane_b32 s40, v0, 56
	v_readlane_b32 s41, v0, 28
	v_readlane_b32 s42, v0, 60
	v_mov_b32_e32 v0, s2
	v_mov_b32_e32 v2, s3
	v_cndmask_b32_e64 v0, v0, v2, s[6:7]
	v_mad_i64_i32 v[2:3], s[2:3], v0, s28, v[118:119]
	global_load_dwordx2 v[36:37], v[2:3], off offset:16
	global_load_dwordx4 v[32:35], v[2:3], off
	v_mov_b32_e32 v2, s25
	v_mov_b32_e32 v3, s26
	v_cndmask_b32_e64 v2, v2, v3, s[6:7]
	v_mad_i64_i32 v[4:5], s[2:3], v2, s28, v[118:119]
	global_load_dwordx2 v[42:43], v[4:5], off offset:16
	global_load_dwordx4 v[38:41], v[4:5], off
	v_mov_b32_e32 v3, s27
	v_mov_b32_e32 v4, s30
	v_cndmask_b32_e64 v3, v3, v4, s[6:7]
	v_mad_i64_i32 v[4:5], s[2:3], v3, s28, v[118:119]
	global_load_dwordx2 v[48:49], v[4:5], off offset:16
	global_load_dwordx4 v[44:47], v[4:5], off
	v_mov_b32_e32 v4, s31
	v_mov_b32_e32 v5, s34
	v_cndmask_b32_e64 v6, v4, v5, s[6:7]
	v_mad_i64_i32 v[4:5], s[2:3], v6, s28, v[118:119]
	global_load_dwordx2 v[54:55], v[4:5], off offset:16
	global_load_dwordx4 v[50:53], v[4:5], off
	v_mov_b32_e32 v4, s35
	v_mov_b32_e32 v5, s36
	v_cndmask_b32_e64 v7, v4, v5, s[6:7]
	v_mad_i64_i32 v[4:5], s[2:3], v7, s28, v[118:119]
	global_load_dwordx2 v[60:61], v[4:5], off offset:16
	global_load_dwordx4 v[56:59], v[4:5], off
	v_mov_b32_e32 v4, s37
	v_mov_b32_e32 v5, s38
	v_cndmask_b32_e64 v10, v4, v5, s[6:7]
	v_mad_i64_i32 v[4:5], s[2:3], v10, s28, v[118:119]
	global_load_dwordx2 v[66:67], v[4:5], off offset:16
	global_load_dwordx4 v[62:65], v[4:5], off
	v_mov_b32_e32 v4, s39
	v_mov_b32_e32 v5, s40
	v_cndmask_b32_e64 v11, v4, v5, s[6:7]
	v_mad_i64_i32 v[4:5], s[2:3], v11, s28, v[118:119]
	global_load_dwordx2 v[72:73], v[4:5], off offset:16
	global_load_dwordx4 v[68:71], v[4:5], off
	v_mov_b32_e32 v4, s41
	v_mov_b32_e32 v5, s42
	v_cndmask_b32_e64 v14, v4, v5, s[6:7]
	v_mad_i64_i32 v[4:5], s[2:3], v14, s28, v[118:119]
	global_load_dwordx2 v[78:79], v[4:5], off offset:16
	global_load_dwordx4 v[74:77], v[4:5], off
	ds_read_b64 v[16:17], v8
	v_cndmask_b32_e64 v4, v117, v219, s[14:15]
	ds_bpermute_b32 v4, v242, v4
	v_cndmask_b32_e64 v5, v219, v117, s[14:15]
	v_cndmask_b32_e64 v8, v131, v246, s[14:15]
	ds_bpermute_b32 v8, v242, v8
	v_cndmask_b32_e64 v12, v218, v1, s[14:15]
	s_waitcnt lgkmcnt(1)
	v_add_f32_e32 v4, v5, v4
	v_cndmask_b32_e64 v5, v133, v247, s[14:15]
	ds_bpermute_b32 v5, v242, v5
	ds_bpermute_b32 v12, v242, v12
	v_cndmask_b32_e64 v9, v246, v131, s[14:15]
	s_waitcnt lgkmcnt(2)
	v_add_f32_e32 v8, v9, v8
	v_cndmask_b32_e64 v9, v247, v133, s[14:15]
	v_cndmask_b32_e64 v1, v1, v218, s[14:15]
	s_waitcnt lgkmcnt(1)
	v_add_f32_e32 v5, v9, v5
	s_waitcnt lgkmcnt(0)
	v_add_f32_e32 v1, v1, v12
	v_cndmask_b32_e64 v9, v4, v5, s[16:17]
	v_cndmask_b32_e64 v12, v8, v1, s[16:17]
	ds_bpermute_b32 v9, v241, v9
	ds_bpermute_b32 v12, v241, v12
	v_cndmask_b32_e64 v4, v5, v4, s[16:17]
	v_cndmask_b32_e64 v1, v1, v8, s[16:17]
	s_waitcnt lgkmcnt(1)
	v_add_f32_e32 v4, v4, v9
	s_waitcnt lgkmcnt(0)
	v_add_f32_e32 v1, v1, v12
	v_cndmask_b32_e64 v5, v4, v1, s[18:19]
	ds_bpermute_b32 v5, v240, v5
	v_cndmask_b32_e64 v1, v1, v4, s[18:19]
	s_waitcnt lgkmcnt(0)
	v_add_f32_e32 v1, v1, v5
	ds_bpermute_b32 v4, v244, v1
	s_waitcnt lgkmcnt(0)
	v_add_f32_e32 v1, v1, v4
	ds_bpermute_b32 v4, v245, v1
	s_waitcnt lgkmcnt(0)
	v_add_f32_e32 v1, v1, v4
	v_mul_f32_e32 v18, 0x3caaaaab, v1
	v_mul_f32_e32 v16, 0x3f3504f3, v18
	v_cmp_nlt_f32_e64 s[2:3], |v16|, 1.0
	s_and_saveexec_b64 s[26:27], s[2:3]
	s_xor_b64 s[2:3], exec, s[26:27]
	s_cbranch_execz .LBB0_332
	s_mov_b32 s25, 0x378e98ab
	v_fma_f32 v1, |v16|, s25, v233
	s_mov_b32 s25, 0x3b7cd369
	v_fma_f32 v1, |v16|, v1, s25
	s_mov_b32 s25, 0xbcc618b2
	v_fma_f32 v1, |v16|, v1, s25
	s_mov_b32 s25, 0x3dda74e4
	v_fma_f32 v1, |v16|, v1, s25
	s_mov_b32 s25, 0x3f228afd
	v_fma_f32 v1, |v16|, v1, s25
	s_mov_b32 s25, 0x3e03c728
	v_fma_f32 v1, |v16|, v1, s25
	v_fma_f32 v1, |v16|, v1, |v16|
	v_mul_f32_e32 v4, 0xbfb8aa3b, v1
	s_mov_b32 s25, 0xbfb8aa3b
	v_fma_f32 v5, v1, s25, -v4
	v_rndne_f32_e32 v8, v4
	v_fmac_f32_e32 v5, 0xb2a5705f, v1
	v_sub_f32_e32 v4, v4, v8
	v_add_f32_e32 v4, v4, v5
	v_cvt_i32_f32_e32 v5, v8
	v_exp_f32_e32 v4, v4
	s_mov_b32 s25, 0x42ce8ed0
	v_cmp_nlt_f32_e32 vcc, s25, v1
	s_mov_b32 s25, 0xc2b17218
	v_ldexp_f32 v4, v4, v5
	v_cndmask_b32_e32 v4, 0, v4, vcc
	v_cmp_ngt_f32_e32 vcc, s25, v1
	s_nop 1
	v_cndmask_b32_e32 v1, v234, v4, vcc
	v_sub_f32_e32 v19, 1.0, v1

.LBB0_334:
	s_waitcnt vmcnt(8)
	v_cvt_scalef32_pk32_f32_fp6 v[0:31], v[74:79], 1.0
	v_pk_fma_f32 v[2:3], v[2:3], v[170:171], 0 op_sel_hi:[1,1,0]
	v_pk_fma_f32 v[0:1], v[0:1], v[152:153], 0 op_sel_hi:[1,1,0]
	v_pk_fma_f32 v[2:3], v[6:7], v[172:173], v[2:3]
	v_pk_fma_f32 v[0:1], v[4:5], v[148:149], v[0:1]
	v_pk_fma_f32 v[2:3], v[10:11], v[174:175], v[2:3]
	v_pk_fma_f32 v[0:1], v[8:9], v[144:145], v[0:1]
	v_pk_fma_f32 v[2:3], v[14:15], v[178:179], v[2:3]
	v_pk_fma_f32 v[0:1], v[12:13], v[140:141], v[0:1]
	v_pk_fma_f32 v[2:3], v[18:19], v[180:181], v[2:3]
	v_pk_fma_f32 v[0:1], v[16:17], v[168:169], v[0:1]
	v_pk_fma_f32 v[2:3], v[22:23], v[182:183], v[2:3]
	v_pk_fma_f32 v[0:1], v[20:21], v[164:165], v[0:1]
	v_pk_fma_f32 v[2:3], v[26:27], v[184:185], v[2:3]
	v_pk_fma_f32 v[0:1], v[24:25], v[160:161], v[0:1]
	v_pk_fma_f32 v[2:3], v[30:31], v[186:187], v[2:3]
	v_pk_fma_f32 v[0:1], v[28:29], v[156:157], v[0:1]
	v_add_f32_e32 v4, v2, v3
	v_add_f32_e32 v5, v0, v1
	ds_read_b64 v[218:219], v239 offset:3584
	v_add_f32_e32 v74, v4, v5
	v_cvt_scalef32_pk32_f32_fp6 v[0:31], v[68:73], 1.0
	v_pk_fma_f32 v[2:3], v[2:3], v[170:171], 0 op_sel_hi:[1,1,0]
	v_pk_fma_f32 v[0:1], v[0:1], v[152:153], 0 op_sel_hi:[1,1,0]
	v_pk_fma_f32 v[2:3], v[6:7], v[172:173], v[2:3]
	v_pk_fma_f32 v[0:1], v[4:5], v[148:149], v[0:1]
	v_pk_fma_f32 v[2:3], v[10:11], v[174:175], v[2:3]
	v_pk_fma_f32 v[0:1], v[8:9], v[144:145], v[0:1]
	v_pk_fma_f32 v[2:3], v[14:15], v[178:179], v[2:3]
	v_pk_fma_f32 v[0:1], v[12:13], v[140:141], v[0:1]
	v_pk_fma_f32 v[2:3], v[18:19], v[180:181], v[2:3]
	v_pk_fma_f32 v[0:1], v[16:17], v[168:169], v[0:1]
	v_pk_fma_f32 v[2:3], v[22:23], v[182:183], v[2:3]
	v_pk_fma_f32 v[0:1], v[20:21], v[164:165], v[0:1]
	v_pk_fma_f32 v[2:3], v[26:27], v[184:185], v[2:3]
	v_pk_fma_f32 v[0:1], v[24:25], v[160:161], v[0:1]
	v_pk_fma_f32 v[2:3], v[30:31], v[186:187], v[2:3]
	v_pk_fma_f32 v[0:1], v[28:29], v[156:157], v[0:1]
	v_add_f32_e32 v4, v2, v3
	v_add_f32_e32 v5, v0, v1
	v_add_f32_e32 v68, v4, v5
	v_cvt_scalef32_pk32_f32_fp6 v[0:31], v[62:67], 1.0
	v_pk_fma_f32 v[2:3], v[2:3], v[170:171], 0 op_sel_hi:[1,1,0]
	v_pk_fma_f32 v[0:1], v[0:1], v[152:153], 0 op_sel_hi:[1,1,0]
	v_pk_fma_f32 v[2:3], v[6:7], v[172:173], v[2:3]
	v_pk_fma_f32 v[0:1], v[4:5], v[148:149], v[0:1]
	v_pk_fma_f32 v[2:3], v[10:11], v[174:175], v[2:3]
	v_pk_fma_f32 v[0:1], v[8:9], v[144:145], v[0:1]
	v_pk_fma_f32 v[2:3], v[14:15], v[178:179], v[2:3]
	v_pk_fma_f32 v[0:1], v[12:13], v[140:141], v[0:1]
	v_pk_fma_f32 v[2:3], v[18:19], v[180:181], v[2:3]
	v_pk_fma_f32 v[0:1], v[16:17], v[168:169], v[0:1]
	v_pk_fma_f32 v[2:3], v[22:23], v[182:183], v[2:3]
	v_pk_fma_f32 v[0:1], v[20:21], v[164:165], v[0:1]
	v_pk_fma_f32 v[2:3], v[26:27], v[184:185], v[2:3]
	v_pk_fma_f32 v[0:1], v[24:25], v[160:161], v[0:1]
	v_pk_fma_f32 v[2:3], v[30:31], v[186:187], v[2:3]
	v_pk_fma_f32 v[0:1], v[28:29], v[156:157], v[0:1]
	v_add_f32_e32 v4, v2, v3
	v_add_f32_e32 v5, v0, v1
	v_add_f32_e32 v62, v4, v5
	v_cvt_scalef32_pk32_f32_fp6 v[0:31], v[56:61], 1.0
	v_pk_fma_f32 v[2:3], v[2:3], v[170:171], 0 op_sel_hi:[1,1,0]
	v_pk_fma_f32 v[0:1], v[0:1], v[152:153], 0 op_sel_hi:[1,1,0]
	v_pk_fma_f32 v[2:3], v[6:7], v[172:173], v[2:3]
	v_pk_fma_f32 v[0:1], v[4:5], v[148:149], v[0:1]
	v_pk_fma_f32 v[2:3], v[10:11], v[174:175], v[2:3]
	v_pk_fma_f32 v[0:1], v[8:9], v[144:145], v[0:1]
	v_pk_fma_f32 v[2:3], v[14:15], v[178:179], v[2:3]
	v_pk_fma_f32 v[0:1], v[12:13], v[140:141], v[0:1]
	v_pk_fma_f32 v[2:3], v[18:19], v[180:181], v[2:3]
	v_pk_fma_f32 v[0:1], v[16:17], v[168:169], v[0:1]
	v_pk_fma_f32 v[2:3], v[22:23], v[182:183], v[2:3]
	v_pk_fma_f32 v[0:1], v[20:21], v[164:165], v[0:1]
	v_pk_fma_f32 v[2:3], v[26:27], v[184:185], v[2:3]
	v_pk_fma_f32 v[0:1], v[24:25], v[160:161], v[0:1]
	v_pk_fma_f32 v[2:3], v[30:31], v[186:187], v[2:3]
	v_pk_fma_f32 v[0:1], v[28:29], v[156:157], v[0:1]
	v_add_f32_e32 v4, v2, v3
	v_add_f32_e32 v5, v0, v1
	v_add_f32_e32 v56, v4, v5
	v_cvt_scalef32_pk32_f32_fp6 v[0:31], v[50:55], 1.0
	v_pk_fma_f32 v[2:3], v[2:3], v[170:171], 0 op_sel_hi:[1,1,0]
	v_pk_fma_f32 v[0:1], v[0:1], v[152:153], 0 op_sel_hi:[1,1,0]
	v_pk_fma_f32 v[2:3], v[6:7], v[172:173], v[2:3]
	v_pk_fma_f32 v[0:1], v[4:5], v[148:149], v[0:1]
	v_pk_fma_f32 v[2:3], v[10:11], v[174:175], v[2:3]
	v_pk_fma_f32 v[0:1], v[8:9], v[144:145], v[0:1]
	v_pk_fma_f32 v[2:3], v[14:15], v[178:179], v[2:3]
	v_pk_fma_f32 v[0:1], v[12:13], v[140:141], v[0:1]
	v_pk_fma_f32 v[2:3], v[18:19], v[180:181], v[2:3]
	v_pk_fma_f32 v[0:1], v[16:17], v[168:169], v[0:1]
	v_pk_fma_f32 v[2:3], v[22:23], v[182:183], v[2:3]
	v_pk_fma_f32 v[0:1], v[20:21], v[164:165], v[0:1]
	v_pk_fma_f32 v[2:3], v[26:27], v[184:185], v[2:3]
	v_pk_fma_f32 v[0:1], v[24:25], v[160:161], v[0:1]
	v_pk_fma_f32 v[2:3], v[30:31], v[186:187], v[2:3]
	v_pk_fma_f32 v[0:1], v[28:29], v[156:157], v[0:1]
	v_add_f32_e32 v4, v2, v3
	v_add_f32_e32 v5, v0, v1
	v_add_f32_e32 v50, v4, v5
	v_cvt_scalef32_pk32_f32_fp6 v[0:31], v[44:49], 1.0
	v_pk_fma_f32 v[2:3], v[2:3], v[170:171], 0 op_sel_hi:[1,1,0]
	v_pk_fma_f32 v[0:1], v[0:1], v[152:153], 0 op_sel_hi:[1,1,0]
	v_pk_fma_f32 v[2:3], v[6:7], v[172:173], v[2:3]
	v_pk_fma_f32 v[0:1], v[4:5], v[148:149], v[0:1]
	v_pk_fma_f32 v[2:3], v[10:11], v[174:175], v[2:3]
	v_pk_fma_f32 v[0:1], v[8:9], v[144:145], v[0:1]
	v_pk_fma_f32 v[2:3], v[14:15], v[178:179], v[2:3]
	v_pk_fma_f32 v[0:1], v[12:13], v[140:141], v[0:1]
	v_pk_fma_f32 v[2:3], v[18:19], v[180:181], v[2:3]
	v_pk_fma_f32 v[0:1], v[16:17], v[168:169], v[0:1]
	v_pk_fma_f32 v[2:3], v[22:23], v[182:183], v[2:3]
	v_pk_fma_f32 v[0:1], v[20:21], v[164:165], v[0:1]
	v_pk_fma_f32 v[2:3], v[26:27], v[184:185], v[2:3]
	v_pk_fma_f32 v[0:1], v[24:25], v[160:161], v[0:1]
	v_pk_fma_f32 v[2:3], v[30:31], v[186:187], v[2:3]
	v_pk_fma_f32 v[0:1], v[28:29], v[156:157], v[0:1]
	v_add_f32_e32 v4, v2, v3
	v_add_f32_e32 v5, v0, v1
	v_add_f32_e32 v44, v4, v5
	v_cvt_scalef32_pk32_f32_fp6 v[0:31], v[38:43], 1.0
	v_pk_fma_f32 v[2:3], v[2:3], v[170:171], 0 op_sel_hi:[1,1,0]
	v_pk_fma_f32 v[0:1], v[0:1], v[152:153], 0 op_sel_hi:[1,1,0]
	v_pk_fma_f32 v[2:3], v[6:7], v[172:173], v[2:3]
	v_pk_fma_f32 v[0:1], v[4:5], v[148:149], v[0:1]
	v_pk_fma_f32 v[2:3], v[10:11], v[174:175], v[2:3]
	v_pk_fma_f32 v[0:1], v[8:9], v[144:145], v[0:1]
	v_pk_fma_f32 v[2:3], v[14:15], v[178:179], v[2:3]
	v_pk_fma_f32 v[0:1], v[12:13], v[140:141], v[0:1]
	v_pk_fma_f32 v[2:3], v[18:19], v[180:181], v[2:3]
	v_pk_fma_f32 v[0:1], v[16:17], v[168:169], v[0:1]
	v_pk_fma_f32 v[2:3], v[22:23], v[182:183], v[2:3]
	v_pk_fma_f32 v[0:1], v[20:21], v[164:165], v[0:1]
	v_pk_fma_f32 v[2:3], v[26:27], v[184:185], v[2:3]
	v_pk_fma_f32 v[0:1], v[24:25], v[160:161], v[0:1]
	v_pk_fma_f32 v[2:3], v[30:31], v[186:187], v[2:3]
	v_pk_fma_f32 v[0:1], v[28:29], v[156:157], v[0:1]
	v_add_f32_e32 v4, v2, v3
	v_add_f32_e32 v5, v0, v1
	v_add_f32_e32 v38, v4, v5
	v_cvt_scalef32_pk32_f32_fp6 v[0:31], v[32:37], 1.0
	v_pk_fma_f32 v[2:3], v[2:3], v[170:171], 0 op_sel_hi:[1,1,0]
	v_pk_fma_f32 v[0:1], v[0:1], v[152:153], 0 op_sel_hi:[1,1,0]
	v_pk_fma_f32 v[2:3], v[6:7], v[172:173], v[2:3]
	v_pk_fma_f32 v[0:1], v[4:5], v[148:149], v[0:1]
	v_pk_fma_f32 v[2:3], v[10:11], v[174:175], v[2:3]
	v_pk_fma_f32 v[0:1], v[8:9], v[144:145], v[0:1]
	v_pk_fma_f32 v[2:3], v[14:15], v[178:179], v[2:3]
	v_pk_fma_f32 v[0:1], v[12:13], v[140:141], v[0:1]
	v_pk_fma_f32 v[2:3], v[18:19], v[180:181], v[2:3]
	v_pk_fma_f32 v[0:1], v[16:17], v[168:169], v[0:1]
	v_pk_fma_f32 v[2:3], v[22:23], v[182:183], v[2:3]
	v_pk_fma_f32 v[0:1], v[20:21], v[164:165], v[0:1]
	v_pk_fma_f32 v[2:3], v[26:27], v[184:185], v[2:3]
	v_pk_fma_f32 v[0:1], v[24:25], v[160:161], v[0:1]
	v_pk_fma_f32 v[2:3], v[30:31], v[186:187], v[2:3]
	v_pk_fma_f32 v[0:1], v[28:29], v[156:157], v[0:1]
	v_add_f32_e32 v4, v2, v3
	v_add_f32_e32 v5, v0, v1
	v_add_f32_e32 v0, v4, v5
	v_cndmask_b32_e64 v1, v0, v56, s[14:15]
	ds_bpermute_b32 v1, v242, v1
	v_cndmask_b32_e64 v0, v56, v0, s[14:15]
	v_cndmask_b32_e64 v2, v38, v62, s[14:15]
	ds_bpermute_b32 v2, v242, v2
	v_cndmask_b32_e64 v4, v50, v74, s[14:15]
	s_waitcnt lgkmcnt(1)
	v_add_f32_e32 v0, v0, v1
	v_cndmask_b32_e64 v1, v44, v68, s[14:15]
	ds_bpermute_b32 v1, v242, v1
	ds_bpermute_b32 v4, v242, v4
	v_cndmask_b32_e64 v3, v62, v38, s[14:15]
	s_waitcnt lgkmcnt(2)
	v_add_f32_e32 v2, v3, v2
	v_cndmask_b32_e64 v3, v68, v44, s[14:15]
	s_waitcnt lgkmcnt(1)
	v_add_f32_e32 v1, v3, v1
	v_cndmask_b32_e64 v3, v74, v50, s[14:15]
	s_waitcnt lgkmcnt(0)
	v_add_f32_e32 v3, v3, v4
	v_cndmask_b32_e64 v4, v0, v1, s[16:17]
	v_cndmask_b32_e64 v5, v2, v3, s[16:17]
	ds_bpermute_b32 v4, v241, v4
	ds_bpermute_b32 v5, v241, v5
	v_cndmask_b32_e64 v0, v1, v0, s[16:17]
	v_cndmask_b32_e64 v1, v3, v2, s[16:17]
	s_waitcnt lgkmcnt(1)
	v_add_f32_e32 v0, v0, v4
	s_waitcnt lgkmcnt(0)
	v_add_f32_e32 v1, v1, v5
	v_cndmask_b32_e64 v2, v0, v1, s[18:19]
	ds_bpermute_b32 v2, v240, v2
	v_cndmask_b32_e64 v0, v1, v0, s[18:19]
	s_waitcnt lgkmcnt(0)
	v_add_f32_e32 v0, v0, v2
	ds_bpermute_b32 v1, v244, v0
	s_waitcnt lgkmcnt(0)
	v_add_f32_e32 v0, v0, v1
	ds_bpermute_b32 v1, v245, v0
	s_waitcnt lgkmcnt(0)
	v_add_f32_e32 v0, v0, v1
	v_mul_f32_e32 v1, 0x3caaaaab, v0
	v_mul_f32_e32 v0, 0x3f3504f3, v1
	v_cmp_nlt_f32_e64 s[2:3], |v0|, 1.0
	s_and_saveexec_b64 s[24:25], s[2:3]
	s_xor_b64 s[2:3], exec, s[24:25]
	s_cbranch_execz .LBB0_336
	s_mov_b32 s24, 0x378e98ab
	v_fma_f32 v2, |v0|, s24, v233
	s_mov_b32 s24, 0x3b7cd369
	v_fma_f32 v2, |v0|, v2, s24
	s_mov_b32 s24, 0xbcc618b2
	v_fma_f32 v2, |v0|, v2, s24
	s_mov_b32 s24, 0x3dda74e4
	v_fma_f32 v2, |v0|, v2, s24
	s_mov_b32 s24, 0x3f228afd
	v_fma_f32 v2, |v0|, v2, s24
	s_mov_b32 s24, 0x3e03c728
	v_fma_f32 v2, |v0|, v2, s24
	v_fma_f32 v2, |v0|, v2, |v0|
	v_mul_f32_e32 v3, 0xbfb8aa3b, v2
	s_mov_b32 s24, 0xbfb8aa3b
	v_fma_f32 v4, v2, s24, -v3
	v_rndne_f32_e32 v5, v3
	v_fmac_f32_e32 v4, 0xb2a5705f, v2
	v_sub_f32_e32 v3, v3, v5
	v_add_f32_e32 v3, v3, v4
	v_cvt_i32_f32_e32 v4, v5
	v_exp_f32_e32 v3, v3
	s_mov_b32 s24, 0x42ce8ed0
	v_cmp_nlt_f32_e32 vcc, s24, v2
	s_mov_b32 s24, 0xc2b17218
	v_ldexp_f32 v3, v3, v4
	v_cndmask_b32_e32 v3, 0, v3, vcc
	v_cmp_ngt_f32_e32 vcc, s24, v2
	s_nop 1
	v_cndmask_b32_e32 v2, v234, v3, vcc
	v_sub_f32_e32 v2, 1.0, v2
